# code placement: P10 tile loop and the five GEMM K-loop heads aligned to 64 bytes
# speedup vs baseline: 1.0015x; 1.0015x over previous
.LBB0_236:
	s_ashr_i32 s59, s58, 31
	s_xor_b64 s[70:71], s[6:7], -1
	s_lshl_b64 s[28:29], s[58:59], 20
	s_add_u32 s68, s62, s28
	s_addc_u32 s69, s63, s29
	s_and_b64 s[28:29], s[6:7], exec
	s_cselect_b32 s9, s69, s77
	s_cselect_b32 s59, s68, s76
	s_ashr_i32 s61, s60, 31
	s_lshl_b64 s[28:29], s[60:61], 20
	s_add_u32 s72, s64, s28
	s_addc_u32 s73, s65, s29
	s_and_b64 s[28:29], s[6:7], exec
	s_cselect_b32 s61, s73, s79
	s_cselect_b32 s75, s72, s78
	s_bitcmp0_b32 s23, 0
	s_cselect_b64 vcc, -1, 0
	s_add_u32 s76, s76, 0x80080
	s_addc_u32 s77, s77, 0
	s_add_u32 s83, s78, 0x100
	v_mov_b32_e32 v0, 0
	s_addc_u32 s28, s79, 0
	s_mov_b32 s29, -2
	v_mov_b32_e32 v1, v0
	v_mov_b32_e32 v2, v0
	v_mov_b32_e32 v3, v0
	v_mov_b32_e32 v4, v0
	v_mov_b32_e32 v5, v0
	v_mov_b32_e32 v6, v0
	v_mov_b32_e32 v7, v0
	v_mov_b32_e32 v8, v0
	v_mov_b32_e32 v9, v0
	v_mov_b32_e32 v10, v0
	v_mov_b32_e32 v11, v0
	v_mov_b32_e32 v12, v0
	v_mov_b32_e32 v13, v0
	v_mov_b32_e32 v14, v0
	v_mov_b32_e32 v15, v0
	v_mov_b32_e32 v16, v0
	v_mov_b32_e32 v17, v0
	v_mov_b32_e32 v18, v0
	v_mov_b32_e32 v19, v0
	v_mov_b32_e32 v20, v0
	v_mov_b32_e32 v21, v0
	v_mov_b32_e32 v22, v0
	v_mov_b32_e32 v23, v0
	v_mov_b32_e32 v24, v0
	v_mov_b32_e32 v25, v0
	v_mov_b32_e32 v26, v0
	v_mov_b32_e32 v27, v0
	v_mov_b32_e32 v28, v0
	v_mov_b32_e32 v29, v0
	v_mov_b32_e32 v30, v0
	v_mov_b32_e32 v31, v0
	v_mov_b32_e32 v64, v0
	v_mov_b32_e32 v65, v0
	v_mov_b32_e32 v66, v0
	v_mov_b32_e32 v67, v0
	v_mov_b32_e32 v68, v0
	v_mov_b32_e32 v69, v0
	v_mov_b32_e32 v70, v0
	v_mov_b32_e32 v71, v0
	v_mov_b32_e32 v72, v0
	v_mov_b32_e32 v73, v0
	v_mov_b32_e32 v74, v0
	v_mov_b32_e32 v75, v0
	v_mov_b32_e32 v76, v0
	v_mov_b32_e32 v77, v0
	v_mov_b32_e32 v78, v0
	v_mov_b32_e32 v79, v0
	v_mov_b32_e32 v80, v0
	v_mov_b32_e32 v81, v0
	v_mov_b32_e32 v82, v0
	v_mov_b32_e32 v83, v0
	v_mov_b32_e32 v84, v0
	v_mov_b32_e32 v85, v0
	v_mov_b32_e32 v86, v0
	v_mov_b32_e32 v87, v0
	v_mov_b32_e32 v88, v0
	v_mov_b32_e32 v89, v0
	v_mov_b32_e32 v90, v0
	v_mov_b32_e32 v91, v0
	v_mov_b32_e32 v92, v0
	v_mov_b32_e32 v93, v0
	v_mov_b32_e32 v94, v0
	v_mov_b32_e32 v95, v0
	v_mov_b32_e32 v32, v0
	v_mov_b32_e32 v33, v0
	v_mov_b32_e32 v34, v0
	v_mov_b32_e32 v35, v0
	v_mov_b32_e32 v36, v0
	v_mov_b32_e32 v37, v0
	v_mov_b32_e32 v38, v0
	v_mov_b32_e32 v39, v0
	v_mov_b32_e32 v40, v0
	v_mov_b32_e32 v41, v0
	v_mov_b32_e32 v42, v0
	v_mov_b32_e32 v43, v0
	v_mov_b32_e32 v44, v0
	v_mov_b32_e32 v45, v0
	v_mov_b32_e32 v46, v0
	v_mov_b32_e32 v47, v0
	v_mov_b32_e32 v48, v0
	v_mov_b32_e32 v49, v0
	v_mov_b32_e32 v50, v0
	v_mov_b32_e32 v51, v0
	v_mov_b32_e32 v52, v0
	v_mov_b32_e32 v53, v0
	v_mov_b32_e32 v54, v0
	v_mov_b32_e32 v55, v0
	v_mov_b32_e32 v56, v0
	v_mov_b32_e32 v57, v0
	v_mov_b32_e32 v58, v0
	v_mov_b32_e32 v59, v0
	v_mov_b32_e32 v60, v0
	v_mov_b32_e32 v61, v0
	v_mov_b32_e32 v62, v0
	v_mov_b32_e32 v63, v0
	v_mov_b32_e32 v96, v0
	v_mov_b32_e32 v97, v0
	v_mov_b32_e32 v98, v0
	v_mov_b32_e32 v99, v0
	v_mov_b32_e32 v100, v0
	v_mov_b32_e32 v101, v0
	v_mov_b32_e32 v102, v0
	v_mov_b32_e32 v103, v0
	v_mov_b32_e32 v104, v0
	v_mov_b32_e32 v105, v0
	v_mov_b32_e32 v106, v0
	v_mov_b32_e32 v107, v0
	v_mov_b32_e32 v108, v0
	v_mov_b32_e32 v109, v0
	v_mov_b32_e32 v110, v0
	v_mov_b32_e32 v111, v0
	v_mov_b32_e32 v112, v0
	v_mov_b32_e32 v113, v0
	v_mov_b32_e32 v114, v0
	v_mov_b32_e32 v115, v0
	v_mov_b32_e32 v116, v0
	v_mov_b32_e32 v117, v0
	v_mov_b32_e32 v118, v0
	v_mov_b32_e32 v119, v0
	v_mov_b32_e32 v120, v0
	v_mov_b32_e32 v121, v0
	v_mov_b32_e32 v122, v0
	v_mov_b32_e32 v123, v0
	v_mov_b32_e32 v124, v0
	v_mov_b32_e32 v125, v0
	v_mov_b32_e32 v126, v0
	v_mov_b32_e32 v127, v0
	v_cndmask_b32_e32 v173, v164, v163, vcc
	v_cndmask_b32_e32 v174, v166, v165, vcc
	.p2align	6

.LBB0_693:
	s_ashr_i32 s27, s26, 31
	v_cmp_lt_i64_e32 vcc, s[28:29], v[140:141]
	s_lshl_b64 s[28:29], s[26:27], 20
	s_add_u32 s28, s52, s28
	s_addc_u32 s29, s53, s29
	s_and_b64 s[30:31], vcc, exec
	s_cselect_b32 s27, s29, s35
	s_cselect_b32 s73, s28, s34
	s_ashr_i32 s25, s24, 31
	s_lshl_b64 s[30:31], s[24:25], 20
	s_add_u32 s30, s54, s30
	s_addc_u32 s31, s55, s31
	s_and_b64 s[38:39], vcc, exec
	s_cselect_b32 s25, s31, s37
	s_cselect_b32 s74, s30, s36
	s_add_u32 s34, s34, 0x80080
	s_addc_u32 s35, s35, 0
	s_add_u32 s75, s36, 0x100
	v_mov_b32_e32 v0, 0
	s_addc_u32 s76, s37, 0
	s_mov_b32 s77, -2
	v_mov_b32_e32 v1, v0
	v_mov_b32_e32 v2, v0
	v_mov_b32_e32 v3, v0
	v_mov_b32_e32 v4, v0
	v_mov_b32_e32 v5, v0
	v_mov_b32_e32 v6, v0
	v_mov_b32_e32 v7, v0
	v_mov_b32_e32 v8, v0
	v_mov_b32_e32 v9, v0
	v_mov_b32_e32 v10, v0
	v_mov_b32_e32 v11, v0
	v_mov_b32_e32 v12, v0
	v_mov_b32_e32 v13, v0
	v_mov_b32_e32 v14, v0
	v_mov_b32_e32 v15, v0
	v_mov_b32_e32 v16, v0
	v_mov_b32_e32 v17, v0
	v_mov_b32_e32 v18, v0
	v_mov_b32_e32 v19, v0
	v_mov_b32_e32 v20, v0
	v_mov_b32_e32 v21, v0
	v_mov_b32_e32 v22, v0
	v_mov_b32_e32 v23, v0
	v_mov_b32_e32 v24, v0
	v_mov_b32_e32 v25, v0
	v_mov_b32_e32 v26, v0
	v_mov_b32_e32 v27, v0
	v_mov_b32_e32 v28, v0
	v_mov_b32_e32 v29, v0
	v_mov_b32_e32 v30, v0
	v_mov_b32_e32 v31, v0
	v_mov_b32_e32 v40, v0
	v_mov_b32_e32 v41, v0
	v_mov_b32_e32 v42, v0
	v_mov_b32_e32 v43, v0
	v_mov_b32_e32 v44, v0
	v_mov_b32_e32 v45, v0
	v_mov_b32_e32 v46, v0
	v_mov_b32_e32 v47, v0
	v_mov_b32_e32 v56, v0
	v_mov_b32_e32 v57, v0
	v_mov_b32_e32 v58, v0
	v_mov_b32_e32 v59, v0
	v_mov_b32_e32 v64, v0
	v_mov_b32_e32 v65, v0
	v_mov_b32_e32 v66, v0
	v_mov_b32_e32 v67, v0
	v_mov_b32_e32 v76, v0
	v_mov_b32_e32 v77, v0
	v_mov_b32_e32 v78, v0
	v_mov_b32_e32 v79, v0
	v_mov_b32_e32 v84, v0
	v_mov_b32_e32 v85, v0
	v_mov_b32_e32 v86, v0
	v_mov_b32_e32 v87, v0
	v_mov_b32_e32 v88, v0
	v_mov_b32_e32 v89, v0
	v_mov_b32_e32 v90, v0
	v_mov_b32_e32 v91, v0
	v_mov_b32_e32 v92, v0
	v_mov_b32_e32 v93, v0
	v_mov_b32_e32 v94, v0
	v_mov_b32_e32 v95, v0
	v_mov_b32_e32 v32, v0
	v_mov_b32_e32 v33, v0
	v_mov_b32_e32 v34, v0
	v_mov_b32_e32 v35, v0
	v_mov_b32_e32 v36, v0
	v_mov_b32_e32 v37, v0
	v_mov_b32_e32 v38, v0
	v_mov_b32_e32 v39, v0
	v_mov_b32_e32 v48, v0
	v_mov_b32_e32 v49, v0
	v_mov_b32_e32 v50, v0
	v_mov_b32_e32 v51, v0
	v_mov_b32_e32 v52, v0
	v_mov_b32_e32 v53, v0
	v_mov_b32_e32 v54, v0
	v_mov_b32_e32 v55, v0
	v_mov_b32_e32 v60, v0
	v_mov_b32_e32 v61, v0
	v_mov_b32_e32 v62, v0
	v_mov_b32_e32 v63, v0
	v_mov_b32_e32 v68, v0
	v_mov_b32_e32 v69, v0
	v_mov_b32_e32 v70, v0
	v_mov_b32_e32 v71, v0
	v_mov_b32_e32 v72, v0
	v_mov_b32_e32 v73, v0
	v_mov_b32_e32 v74, v0
	v_mov_b32_e32 v75, v0
	v_mov_b32_e32 v80, v0
	v_mov_b32_e32 v81, v0
	v_mov_b32_e32 v82, v0
	v_mov_b32_e32 v83, v0
	v_mov_b32_e32 v96, v0
	v_mov_b32_e32 v97, v0
	v_mov_b32_e32 v98, v0
	v_mov_b32_e32 v99, v0
	v_mov_b32_e32 v100, v0
	v_mov_b32_e32 v101, v0
	v_mov_b32_e32 v102, v0
	v_mov_b32_e32 v103, v0
	v_mov_b32_e32 v104, v0
	v_mov_b32_e32 v105, v0
	v_mov_b32_e32 v106, v0
	v_mov_b32_e32 v107, v0
	v_mov_b32_e32 v108, v0
	v_mov_b32_e32 v109, v0
	v_mov_b32_e32 v110, v0
	v_mov_b32_e32 v111, v0
	v_mov_b32_e32 v112, v0
	v_mov_b32_e32 v113, v0
	v_mov_b32_e32 v114, v0
	v_mov_b32_e32 v115, v0
	v_mov_b32_e32 v116, v0
	v_mov_b32_e32 v117, v0
	v_mov_b32_e32 v118, v0
	v_mov_b32_e32 v119, v0
	v_mov_b32_e32 v120, v0
	v_mov_b32_e32 v121, v0
	v_mov_b32_e32 v122, v0
	v_mov_b32_e32 v123, v0
	v_mov_b32_e32 v124, v0
	v_mov_b32_e32 v125, v0
	v_mov_b32_e32 v126, v0
	v_mov_b32_e32 v127, v0
	.p2align	6

.LBB0_819:
	s_ashr_i32 s19, s18, 31
	v_cmp_lt_i64_e32 vcc, s[20:21], v[140:141]
	s_lshl_b64 s[20:21], s[18:19], 20
	s_add_u32 s20, s35, s20
	s_addc_u32 s21, s36, s21
	s_and_b64 s[22:23], vcc, exec
	s_cselect_b32 s19, s21, s25
	s_cselect_b32 s63, s20, s24
	s_ashr_i32 s15, s14, 31
	s_lshl_b64 s[22:23], s[14:15], 20
	s_add_u32 s22, s31, s22
	s_addc_u32 s23, s34, s23
	s_and_b64 s[28:29], vcc, exec
	s_cselect_b32 s15, s23, s27
	s_cselect_b32 s64, s22, s26
	s_add_u32 s24, s24, 0x80080
	s_addc_u32 s25, s25, 0
	s_add_u32 s65, s26, 0x100
	v_mov_b32_e32 v0, 0
	s_addc_u32 s66, s27, 0
	s_mov_b32 s67, -2
	v_mov_b32_e32 v1, v0
	v_mov_b32_e32 v2, v0
	v_mov_b32_e32 v3, v0
	v_mov_b32_e32 v4, v0
	v_mov_b32_e32 v5, v0
	v_mov_b32_e32 v6, v0
	v_mov_b32_e32 v7, v0
	v_mov_b32_e32 v8, v0
	v_mov_b32_e32 v9, v0
	v_mov_b32_e32 v10, v0
	v_mov_b32_e32 v11, v0
	v_mov_b32_e32 v12, v0
	v_mov_b32_e32 v13, v0
	v_mov_b32_e32 v14, v0
	v_mov_b32_e32 v15, v0
	v_mov_b32_e32 v16, v0
	v_mov_b32_e32 v17, v0
	v_mov_b32_e32 v18, v0
	v_mov_b32_e32 v19, v0
	v_mov_b32_e32 v20, v0
	v_mov_b32_e32 v21, v0
	v_mov_b32_e32 v22, v0
	v_mov_b32_e32 v23, v0
	v_mov_b32_e32 v24, v0
	v_mov_b32_e32 v25, v0
	v_mov_b32_e32 v26, v0
	v_mov_b32_e32 v27, v0
	v_mov_b32_e32 v28, v0
	v_mov_b32_e32 v29, v0
	v_mov_b32_e32 v30, v0
	v_mov_b32_e32 v31, v0
	v_mov_b32_e32 v36, v0
	v_mov_b32_e32 v37, v0
	v_mov_b32_e32 v38, v0
	v_mov_b32_e32 v39, v0
	v_mov_b32_e32 v44, v0
	v_mov_b32_e32 v45, v0
	v_mov_b32_e32 v46, v0
	v_mov_b32_e32 v47, v0
	v_mov_b32_e32 v56, v0
	v_mov_b32_e32 v57, v0
	v_mov_b32_e32 v58, v0
	v_mov_b32_e32 v59, v0
	v_mov_b32_e32 v60, v0
	v_mov_b32_e32 v61, v0
	v_mov_b32_e32 v62, v0
	v_mov_b32_e32 v63, v0
	v_mov_b32_e32 v72, v0
	v_mov_b32_e32 v73, v0
	v_mov_b32_e32 v74, v0
	v_mov_b32_e32 v75, v0
	v_mov_b32_e32 v80, v0
	v_mov_b32_e32 v81, v0
	v_mov_b32_e32 v82, v0
	v_mov_b32_e32 v83, v0
	v_mov_b32_e32 v88, v0
	v_mov_b32_e32 v89, v0
	v_mov_b32_e32 v90, v0
	v_mov_b32_e32 v91, v0
	v_mov_b32_e32 v92, v0
	v_mov_b32_e32 v93, v0
	v_mov_b32_e32 v94, v0
	v_mov_b32_e32 v95, v0
	v_mov_b32_e32 v32, v0
	v_mov_b32_e32 v33, v0
	v_mov_b32_e32 v34, v0
	v_mov_b32_e32 v35, v0
	v_mov_b32_e32 v40, v0
	v_mov_b32_e32 v41, v0
	v_mov_b32_e32 v42, v0
	v_mov_b32_e32 v43, v0
	v_mov_b32_e32 v48, v0
	v_mov_b32_e32 v49, v0
	v_mov_b32_e32 v50, v0
	v_mov_b32_e32 v51, v0
	v_mov_b32_e32 v52, v0
	v_mov_b32_e32 v53, v0
	v_mov_b32_e32 v54, v0
	v_mov_b32_e32 v55, v0
	v_mov_b32_e32 v64, v0
	v_mov_b32_e32 v65, v0
	v_mov_b32_e32 v66, v0
	v_mov_b32_e32 v67, v0
	v_mov_b32_e32 v68, v0
	v_mov_b32_e32 v69, v0
	v_mov_b32_e32 v70, v0
	v_mov_b32_e32 v71, v0
	v_mov_b32_e32 v76, v0
	v_mov_b32_e32 v77, v0
	v_mov_b32_e32 v78, v0
	v_mov_b32_e32 v79, v0
	v_mov_b32_e32 v84, v0
	v_mov_b32_e32 v85, v0
	v_mov_b32_e32 v86, v0
	v_mov_b32_e32 v87, v0
	v_mov_b32_e32 v96, v0
	v_mov_b32_e32 v97, v0
	v_mov_b32_e32 v98, v0
	v_mov_b32_e32 v99, v0
	v_mov_b32_e32 v100, v0
	v_mov_b32_e32 v101, v0
	v_mov_b32_e32 v102, v0
	v_mov_b32_e32 v103, v0
	v_mov_b32_e32 v104, v0
	v_mov_b32_e32 v105, v0
	v_mov_b32_e32 v106, v0
	v_mov_b32_e32 v107, v0
	v_mov_b32_e32 v108, v0
	v_mov_b32_e32 v109, v0
	v_mov_b32_e32 v110, v0
	v_mov_b32_e32 v111, v0
	v_mov_b32_e32 v112, v0
	v_mov_b32_e32 v113, v0
	v_mov_b32_e32 v114, v0
	v_mov_b32_e32 v115, v0
	v_mov_b32_e32 v116, v0
	v_mov_b32_e32 v117, v0
	v_mov_b32_e32 v118, v0
	v_mov_b32_e32 v119, v0
	v_mov_b32_e32 v120, v0
	v_mov_b32_e32 v121, v0
	v_mov_b32_e32 v122, v0
	v_mov_b32_e32 v123, v0
	v_mov_b32_e32 v124, v0
	v_mov_b32_e32 v125, v0
	v_mov_b32_e32 v126, v0
	v_mov_b32_e32 v127, v0
	.p2align	6

.LBB0_1056:
	s_ashr_i32 s37, s36, 31
	s_xor_b64 s[58:59], s[6:7], -1
	s_lshl_b64 s[56:57], s[36:37], 18
	s_add_u32 s56, s54, s56
	s_addc_u32 s57, s55, s57
	s_and_b64 s[60:61], s[6:7], exec
	s_cselect_b32 s9, s57, s65
	s_cselect_b32 s37, s56, s64
	s_ashr_i32 s35, s34, 31
	s_lshl_b64 s[60:61], s[34:35], 18
	s_add_u32 s60, s52, s60
	s_addc_u32 s61, s53, s61
	s_and_b64 s[68:69], s[6:7], exec
	s_cselect_b32 s35, s61, s67
	s_cselect_b32 s63, s60, s66
	s_bitcmp0_b32 s88, 0
	s_cselect_b64 vcc, -1, 0
	s_add_u32 s64, s64, 0x20080
	s_addc_u32 s65, s65, 0
	s_add_u32 s91, s66, 0x100
	v_mov_b32_e32 v0, 0
	v_cndmask_b32_e32 v166, v157, v156, vcc
	v_cndmask_b32_e32 v167, v159, v158, vcc
	s_addc_u32 s92, s67, 0
	s_mov_b32 s93, -2
	v_mov_b32_e32 v1, v0
	v_mov_b32_e32 v2, v0
	v_mov_b32_e32 v3, v0
	v_mov_b32_e32 v4, v0
	v_mov_b32_e32 v5, v0
	v_mov_b32_e32 v6, v0
	v_mov_b32_e32 v7, v0
	v_mov_b32_e32 v8, v0
	v_mov_b32_e32 v9, v0
	v_mov_b32_e32 v10, v0
	v_mov_b32_e32 v11, v0
	v_mov_b32_e32 v12, v0
	v_mov_b32_e32 v13, v0
	v_mov_b32_e32 v14, v0
	v_mov_b32_e32 v15, v0
	v_mov_b32_e32 v16, v0
	s_waitcnt lgkmcnt(0)
	v_mov_b32_e32 v17, v0
	v_mov_b32_e32 v18, v0
	v_mov_b32_e32 v19, v0
	v_mov_b32_e32 v20, v0
	v_mov_b32_e32 v21, v0
	v_mov_b32_e32 v22, v0
	v_mov_b32_e32 v23, v0
	v_mov_b32_e32 v24, v0
	v_mov_b32_e32 v25, v0
	v_mov_b32_e32 v26, v0
	v_mov_b32_e32 v27, v0
	v_mov_b32_e32 v28, v0
	v_mov_b32_e32 v29, v0
	v_mov_b32_e32 v30, v0
	v_mov_b32_e32 v31, v0
	v_mov_b32_e32 v64, v0
	v_mov_b32_e32 v65, v0
	v_mov_b32_e32 v66, v0
	v_mov_b32_e32 v67, v0
	v_mov_b32_e32 v68, v0
	v_mov_b32_e32 v69, v0
	v_mov_b32_e32 v70, v0
	v_mov_b32_e32 v71, v0
	v_mov_b32_e32 v72, v0
	v_mov_b32_e32 v73, v0
	v_mov_b32_e32 v74, v0
	v_mov_b32_e32 v75, v0
	v_mov_b32_e32 v76, v0
	v_mov_b32_e32 v77, v0
	v_mov_b32_e32 v78, v0
	v_mov_b32_e32 v79, v0
	v_mov_b32_e32 v80, v0
	v_mov_b32_e32 v81, v0
	v_mov_b32_e32 v82, v0
	v_mov_b32_e32 v83, v0
	v_mov_b32_e32 v84, v0
	v_mov_b32_e32 v85, v0
	v_mov_b32_e32 v86, v0
	v_mov_b32_e32 v87, v0
	v_mov_b32_e32 v88, v0
	v_mov_b32_e32 v89, v0
	v_mov_b32_e32 v90, v0
	v_mov_b32_e32 v91, v0
	v_mov_b32_e32 v92, v0
	v_mov_b32_e32 v93, v0
	v_mov_b32_e32 v94, v0
	v_mov_b32_e32 v95, v0
	v_mov_b32_e32 v32, v0
	v_mov_b32_e32 v33, v0
	v_mov_b32_e32 v34, v0
	v_mov_b32_e32 v35, v0
	v_mov_b32_e32 v36, v0
	v_mov_b32_e32 v37, v0
	v_mov_b32_e32 v38, v0
	v_mov_b32_e32 v39, v0
	v_mov_b32_e32 v40, v0
	v_mov_b32_e32 v41, v0
	v_mov_b32_e32 v42, v0
	v_mov_b32_e32 v43, v0
	v_mov_b32_e32 v44, v0
	v_mov_b32_e32 v45, v0
	v_mov_b32_e32 v46, v0
	v_mov_b32_e32 v47, v0
	v_mov_b32_e32 v48, v0
	v_mov_b32_e32 v49, v0
	v_mov_b32_e32 v50, v0
	v_mov_b32_e32 v51, v0
	v_mov_b32_e32 v52, v0
	v_mov_b32_e32 v53, v0
	v_mov_b32_e32 v54, v0
	v_mov_b32_e32 v55, v0
	v_mov_b32_e32 v56, v0
	v_mov_b32_e32 v57, v0
	v_mov_b32_e32 v58, v0
	v_mov_b32_e32 v59, v0
	v_mov_b32_e32 v60, v0
	v_mov_b32_e32 v61, v0
	v_mov_b32_e32 v62, v0
	v_mov_b32_e32 v63, v0
	v_mov_b32_e32 v96, v0
	v_mov_b32_e32 v97, v0
	v_mov_b32_e32 v98, v0
	v_mov_b32_e32 v99, v0
	v_mov_b32_e32 v100, v0
	v_mov_b32_e32 v101, v0
	v_mov_b32_e32 v102, v0
	v_mov_b32_e32 v103, v0
	v_mov_b32_e32 v104, v0
	v_mov_b32_e32 v105, v0
	v_mov_b32_e32 v106, v0
	v_mov_b32_e32 v107, v0
	v_mov_b32_e32 v108, v0
	v_mov_b32_e32 v109, v0
	v_mov_b32_e32 v110, v0
	v_mov_b32_e32 v111, v0
	v_mov_b32_e32 v112, v0
	v_mov_b32_e32 v113, v0
	v_mov_b32_e32 v114, v0
	v_mov_b32_e32 v115, v0
	v_mov_b32_e32 v116, v0
	v_mov_b32_e32 v117, v0
	v_mov_b32_e32 v118, v0
	v_mov_b32_e32 v119, v0
	v_mov_b32_e32 v120, v0
	v_mov_b32_e32 v121, v0
	v_mov_b32_e32 v122, v0
	v_mov_b32_e32 v123, v0
	v_mov_b32_e32 v124, v0
	v_mov_b32_e32 v125, v0
	v_mov_b32_e32 v126, v0
	v_mov_b32_e32 v127, v0
	.p2align	6

.LBB0_1312:
	v_pk_add_f32 v[66:67], v[154:155], 0 op_sel_hi:[1,0]
	s_sub_i32 s33, 0x1000, s53
	v_pk_add_f32 v[66:67], v[168:169], v[66:67]
	s_lshr_b32 s53, s33, 6
	v_pk_add_f32 v[66:67], v[170:171], v[66:67]
	s_mul_hi_u32 s33, s84, 0x15555556
	v_pk_add_f32 v[66:67], v[172:173], v[66:67]
	s_lshl_b32 s49, s54, 7
	v_pk_add_f32 v[66:67], v[174:175], v[66:67]
	s_or_b32 s54, s48, 31
	v_pk_add_f32 v[66:67], v[176:177], v[66:67]
	s_lshl_b32 s55, s55, 10
	v_pk_add_f32 v[66:67], v[178:179], v[66:67]
	s_lshl_b32 s82, s82, 10
	v_pk_add_f32 v[66:67], v[180:181], v[66:67]
	s_lshl_b32 s33, s33, 13
	v_pk_add_f32 v[66:67], v[182:183], v[66:67]
	s_add_u32 s33, s87, s33
	v_pk_add_f32 v[66:67], v[184:185], v[66:67]
	s_addc_u32 s84, 0, 0
	v_pk_add_f32 v[66:67], v[186:187], v[66:67]
	s_add_u32 s90, s33, 0x11804100
	v_pk_add_f32 v[66:67], v[188:189], v[66:67]
	s_addc_u32 s91, s84, 0
	v_pk_add_f32 v[66:67], v[190:191], v[66:67]
	s_add_u32 s33, s86, s85
	v_pk_add_f32 v[66:67], v[192:193], v[66:67]
	s_addc_u32 s85, 0, 0
	v_pk_add_f32 v[66:67], v[194:195], v[66:67]
	s_add_u32 s84, s33, 0x19094000
	v_pk_add_f32 v[66:67], v[196:197], v[66:67]
	v_mov_b32_e32 v161, v145
	v_add_f32_e32 v65, v66, v67
	v_mov_b32_e32 v163, v145
	v_mov_b32_e32 v165, v145
	v_mov_b32_e32 v167, v145
	v_mov_b32_e32 v157, v145
	v_mov_b32_e32 v159, v145
	s_addc_u32 s85, s85, 0
	v_add_f32_e32 v184, v64, v65
	v_lshl_add_u64 v[154:155], s[90:91], 0, v[144:145]
	v_lshl_add_u64 v[156:157], s[90:91], 0, v[156:157]
	v_lshl_add_u64 v[158:159], s[90:91], 0, v[158:159]
	v_lshl_add_u64 v[160:161], s[84:85], 0, v[160:161]
	v_lshl_add_u64 v[162:163], s[84:85], 0, v[162:163]
	v_lshl_add_u64 v[164:165], s[84:85], 0, v[164:165]
	v_lshl_add_u64 v[166:167], s[84:85], 0, v[166:167]
	s_mov_b32 s87, 0
	s_movk_i32 s84, 0x7f
	s_mov_b32 s85, 1
	v_mov_b32_e32 v216, v92
	v_mov_b32_e32 v217, v93
	v_mov_b32_e32 v218, v94
	v_mov_b32_e32 v219, v95
	v_mov_b32_e32 v220, v88
	v_mov_b32_e32 v221, v89
	v_mov_b32_e32 v222, v90
	v_mov_b32_e32 v223, v91
	v_mov_b32_e32 v224, v84
	v_mov_b32_e32 v225, v85
	v_mov_b32_e32 v226, v86
	v_mov_b32_e32 v227, v87
	v_mov_b32_e32 v228, v80
	v_mov_b32_e32 v229, v81
	v_mov_b32_e32 v230, v82
	v_mov_b32_e32 v231, v83
	v_mov_b32_e32 v194, 0
	v_mov_b32_e32 v195, 0
	v_mov_b32_e32 v196, 0
	v_mov_b32_e32 v197, 0
	s_mov_b64 s[92:93], s[42:43]
	s_mov_b64 s[94:95], s[42:43]
	.p2align	6

.LBB0_1428:
	s_ashr_i32 s27, s26, 31
	v_cmp_lt_i64_e32 vcc, s[28:29], v[140:141]
	s_lshl_b64 s[28:29], s[26:27], 20
	s_add_u32 s28, s48, s28
	s_addc_u32 s29, s49, s29
	s_and_b64 s[30:31], vcc, exec
	s_cselect_b32 s27, s29, s35
	s_cselect_b32 s69, s28, s34
	s_ashr_i32 s25, s24, 31
	s_lshl_b64 s[30:31], s[24:25], 20
	s_add_u32 s30, s50, s30
	s_addc_u32 s31, s51, s31
	s_and_b64 s[38:39], vcc, exec
	s_cselect_b32 s25, s31, s37
	s_cselect_b32 s70, s30, s36
	s_add_u32 s34, s34, 0x80080
	s_addc_u32 s35, s35, 0
	s_add_u32 s71, s36, 0x100
	v_mov_b32_e32 v0, 0
	s_addc_u32 s72, s37, 0
	s_mov_b32 s73, -2
	v_mov_b32_e32 v1, v0
	v_mov_b32_e32 v2, v0
	v_mov_b32_e32 v3, v0
	v_mov_b32_e32 v4, v0
	v_mov_b32_e32 v5, v0
	v_mov_b32_e32 v6, v0
	v_mov_b32_e32 v7, v0
	v_mov_b32_e32 v8, v0
	v_mov_b32_e32 v9, v0
	v_mov_b32_e32 v10, v0
	v_mov_b32_e32 v11, v0
	v_mov_b32_e32 v12, v0
	v_mov_b32_e32 v13, v0
	v_mov_b32_e32 v14, v0
	v_mov_b32_e32 v15, v0
	v_mov_b32_e32 v16, v0
	s_waitcnt lgkmcnt(0)
	v_mov_b32_e32 v17, v0
	v_mov_b32_e32 v18, v0
	v_mov_b32_e32 v19, v0
	v_mov_b32_e32 v20, v0
	v_mov_b32_e32 v21, v0
	v_mov_b32_e32 v22, v0
	v_mov_b32_e32 v23, v0
	v_mov_b32_e32 v24, v0
	v_mov_b32_e32 v25, v0
	v_mov_b32_e32 v26, v0
	v_mov_b32_e32 v27, v0
	v_mov_b32_e32 v28, v0
	v_mov_b32_e32 v29, v0
	v_mov_b32_e32 v30, v0
	v_mov_b32_e32 v31, v0
	v_mov_b32_e32 v40, v0
	v_mov_b32_e32 v41, v0
	v_mov_b32_e32 v42, v0
	v_mov_b32_e32 v43, v0
	v_mov_b32_e32 v44, v0
	v_mov_b32_e32 v45, v0
	v_mov_b32_e32 v46, v0
	v_mov_b32_e32 v47, v0
	v_mov_b32_e32 v56, v0
	v_mov_b32_e32 v57, v0
	v_mov_b32_e32 v58, v0
	v_mov_b32_e32 v59, v0
	v_mov_b32_e32 v64, v0
	v_mov_b32_e32 v65, v0
	v_mov_b32_e32 v66, v0
	v_mov_b32_e32 v67, v0
	v_mov_b32_e32 v76, v0
	v_mov_b32_e32 v77, v0
	v_mov_b32_e32 v78, v0
	v_mov_b32_e32 v79, v0
	v_mov_b32_e32 v84, v0
	v_mov_b32_e32 v85, v0
	v_mov_b32_e32 v86, v0
	v_mov_b32_e32 v87, v0
	v_mov_b32_e32 v88, v0
	v_mov_b32_e32 v89, v0
	v_mov_b32_e32 v90, v0
	v_mov_b32_e32 v91, v0
	v_mov_b32_e32 v92, v0
	v_mov_b32_e32 v93, v0
	v_mov_b32_e32 v94, v0
	v_mov_b32_e32 v95, v0
	v_mov_b32_e32 v32, v0
	v_mov_b32_e32 v33, v0
	v_mov_b32_e32 v34, v0
	v_mov_b32_e32 v35, v0
	v_mov_b32_e32 v36, v0
	v_mov_b32_e32 v37, v0
	v_mov_b32_e32 v38, v0
	v_mov_b32_e32 v39, v0
	v_mov_b32_e32 v48, v0
	v_mov_b32_e32 v49, v0
	v_mov_b32_e32 v50, v0
	v_mov_b32_e32 v51, v0
	v_mov_b32_e32 v52, v0
	v_mov_b32_e32 v53, v0
	v_mov_b32_e32 v54, v0
	v_mov_b32_e32 v55, v0
	v_mov_b32_e32 v60, v0
	v_mov_b32_e32 v61, v0
	v_mov_b32_e32 v62, v0
	v_mov_b32_e32 v63, v0
	v_mov_b32_e32 v68, v0
	v_mov_b32_e32 v69, v0
	v_mov_b32_e32 v70, v0
	v_mov_b32_e32 v71, v0
	v_mov_b32_e32 v72, v0
	v_mov_b32_e32 v73, v0
	v_mov_b32_e32 v74, v0
	v_mov_b32_e32 v75, v0
	v_mov_b32_e32 v80, v0
	v_mov_b32_e32 v81, v0
	v_mov_b32_e32 v82, v0
	v_mov_b32_e32 v83, v0
	v_mov_b32_e32 v96, v0
	v_mov_b32_e32 v97, v0
	v_mov_b32_e32 v98, v0
	v_mov_b32_e32 v99, v0
	v_mov_b32_e32 v100, v0
	v_mov_b32_e32 v101, v0
	v_mov_b32_e32 v102, v0
	v_mov_b32_e32 v103, v0
	v_mov_b32_e32 v104, v0
	v_mov_b32_e32 v105, v0
	v_mov_b32_e32 v106, v0
	v_mov_b32_e32 v107, v0
	v_mov_b32_e32 v108, v0
	v_mov_b32_e32 v109, v0
	v_mov_b32_e32 v110, v0
	v_mov_b32_e32 v111, v0
	v_mov_b32_e32 v112, v0
	v_mov_b32_e32 v113, v0
	v_mov_b32_e32 v114, v0
	v_mov_b32_e32 v115, v0
	v_mov_b32_e32 v116, v0
	v_mov_b32_e32 v117, v0
	v_mov_b32_e32 v118, v0
	v_mov_b32_e32 v119, v0
	v_mov_b32_e32 v120, v0
	v_mov_b32_e32 v121, v0
	v_mov_b32_e32 v122, v0
	v_mov_b32_e32 v123, v0
	v_mov_b32_e32 v124, v0
	v_mov_b32_e32 v125, v0
	v_mov_b32_e32 v126, v0
	v_mov_b32_e32 v127, v0
	.p2align	6
